# non-temporal hint on the once-streamed residual loads / output stores of the out-projection epilogue and the final norm
# speedup vs baseline: 1.0102x; 1.0045x over previous
.LBB0_770:
	v_lshrrev_b32_e32 v131, 2, v198
	v_and_b32_e32 v130, 0xc0, v198
	v_and_b32_e32 v131, 12, v131
	v_or3_b32 v146, v130, v131, s14
	v_ashrrev_i32_e32 v130, 1, v198
	v_and_b32_e32 v130, 0xffffff80, v130
	v_lshl_add_u32 v134, s30, 8, v130
	v_and_or_b32 v132, v198, 15, v134
	v_ashrrev_i32_e32 v128, 13, v134
	v_mul_i32_i24_e32 v134, 0xc00, v128
	v_ashrrev_i32_e32 v133, 31, v132
	v_ashrrev_i32_e32 v135, 31, v134
	v_ashrrev_i32_e32 v147, 31, v146
	v_lshlrev_b64 v[130:131], 12, v[132:133]
	v_lshl_add_u64 v[134:135], v[134:135], 2, s[6:7]
	v_lshl_add_u64 v[134:135], v[134:135], 0, s[12:13]
	v_lshlrev_b64 v[136:137], 2, v[146:147]
	v_lshl_add_u64 v[148:149], v[134:135], 0, v[136:137]
	v_lshl_add_u64 v[150:151], s[2:3], 0, v[130:131]
	v_lshl_add_u64 v[150:151], v[150:151], 0, v[136:137]
	v_lshl_add_u64 v[154:155], s[4:5], 0, v[130:131]
	v_lshl_add_u64 v[154:155], v[154:155], 0, v[136:137]
	global_load_dwordx4 v[138:141], v[148:149], off
	global_load_dwordx4 v[142:145], v[148:149], off offset:64
	global_load_dwordx4 v[156:159], v[148:149], off offset:128
	global_load_dwordx4 v[160:163], v[148:149], off offset:192
	global_load_dwordx4 v[164:167], v[150:151], off nt
	global_load_dwordx4 v[168:171], v[150:151], off offset:64 nt
	global_load_dwordx4 v[172:175], v[150:151], off offset:128 nt
	global_load_dwordx4 v[242:245], v[150:151], off offset:192 nt
	v_add_co_u32_e32 v150, vcc, 0x10000, v150
	s_nop 1
	v_addc_co_u32_e32 v151, vcc, 0, v151, vcc
	global_load_dwordx4 v[246:249], v[150:151], off nt
	global_load_dwordx4 v[250:253], v[150:151], off offset:64 nt
	s_waitcnt vmcnt(5)
	v_pk_fma_f32 v[126:127], v[126:127], v[140:141], v[166:167]
	v_pk_fma_f32 v[124:125], v[124:125], v[138:139], v[164:165]
	global_store_dwordx4 v[154:155], v[124:127], off nt
	global_load_dwordx4 v[164:167], v[150:151], off offset:128 nt
	s_waitcnt vmcnt(6)
	v_pk_fma_f32 v[122:123], v[122:123], v[144:145], v[170:171]
	v_pk_fma_f32 v[120:121], v[120:121], v[142:143], v[168:169]
	global_store_dwordx4 v[154:155], v[120:123], off offset:64 nt
	global_load_dwordx4 v[168:171], v[150:151], off offset:192 nt
	v_add_co_u32_e32 v150, vcc, 0x10000, v150
	s_nop 1
	v_addc_co_u32_e32 v151, vcc, 0, v151, vcc
	s_waitcnt vmcnt(7)
	v_pk_fma_f32 v[118:119], v[118:119], v[158:159], v[174:175]
	v_pk_fma_f32 v[116:117], v[116:117], v[156:157], v[172:173]
	global_store_dwordx4 v[154:155], v[116:119], off offset:128 nt
	global_load_dwordx4 v[172:175], v[150:151], off nt
	s_waitcnt vmcnt(8)
	v_pk_fma_f32 v[114:115], v[114:115], v[162:163], v[244:245]
	v_pk_fma_f32 v[112:113], v[112:113], v[160:161], v[242:243]
	global_store_dwordx4 v[154:155], v[112:115], off offset:192 nt
	s_nop 0
	v_add_co_u32_e32 v154, vcc, 0x10000, v154
	s_nop 1
	v_addc_co_u32_e32 v155, vcc, 0, v155, vcc
	global_load_dwordx4 v[242:245], v[150:151], off offset:64 nt
	s_waitcnt vmcnt(9)
	v_pk_fma_f32 v[110:111], v[110:111], v[140:141], v[248:249]
	v_pk_fma_f32 v[108:109], v[108:109], v[138:139], v[246:247]
	global_store_dwordx4 v[154:155], v[108:111], off nt
	global_load_dwordx4 v[246:249], v[150:151], off offset:128 nt
	s_waitcnt vmcnt(10)
	v_pk_fma_f32 v[106:107], v[106:107], v[144:145], v[252:253]
	v_pk_fma_f32 v[104:105], v[104:105], v[142:143], v[250:251]
	global_store_dwordx4 v[154:155], v[104:107], off offset:64 nt
	global_load_dwordx4 v[250:253], v[150:151], off offset:192 nt
	v_add_co_u32_e32 v150, vcc, 0x10000, v150
	s_nop 1
	v_addc_co_u32_e32 v151, vcc, 0, v151, vcc
	s_waitcnt vmcnt(10)
	v_pk_fma_f32 v[102:103], v[102:103], v[158:159], v[166:167]
	v_pk_fma_f32 v[100:101], v[100:101], v[156:157], v[164:165]
	global_store_dwordx4 v[154:155], v[100:103], off offset:128 nt
	global_load_dwordx4 v[164:167], v[150:151], off nt
	s_waitcnt vmcnt(10)
	v_pk_fma_f32 v[98:99], v[98:99], v[162:163], v[170:171]
	v_pk_fma_f32 v[96:97], v[96:97], v[160:161], v[168:169]
	global_store_dwordx4 v[154:155], v[96:99], off offset:192 nt
	s_nop 0
	v_add_co_u32_e32 v154, vcc, 0x10000, v154
	s_nop 1
	v_addc_co_u32_e32 v155, vcc, 0, v155, vcc
	global_load_dwordx4 v[168:171], v[150:151], off offset:64 nt
	s_waitcnt vmcnt(10)
	v_pk_fma_f32 v[94:95], v[94:95], v[140:141], v[174:175]
	v_pk_fma_f32 v[92:93], v[92:93], v[138:139], v[172:173]
	global_store_dwordx4 v[154:155], v[92:95], off nt
	global_load_dwordx4 v[172:175], v[150:151], off offset:128 nt
	s_waitcnt vmcnt(10)
	v_pk_fma_f32 v[90:91], v[90:91], v[144:145], v[244:245]
	v_pk_fma_f32 v[88:89], v[88:89], v[142:143], v[242:243]
	global_store_dwordx4 v[154:155], v[88:91], off offset:64 nt
	global_load_dwordx4 v[242:245], v[150:151], off offset:192 nt
	v_add_co_u32_e32 v150, vcc, 0x10000, v150
	s_nop 1
	v_addc_co_u32_e32 v151, vcc, 0, v151, vcc
	s_waitcnt vmcnt(10)
	v_pk_fma_f32 v[86:87], v[86:87], v[158:159], v[248:249]
	v_pk_fma_f32 v[84:85], v[84:85], v[156:157], v[246:247]
	global_store_dwordx4 v[154:155], v[84:87], off offset:128 nt
	global_load_dwordx4 v[246:249], v[150:151], off nt
	s_waitcnt vmcnt(10)
	v_pk_fma_f32 v[82:83], v[82:83], v[162:163], v[252:253]
	v_pk_fma_f32 v[80:81], v[80:81], v[160:161], v[250:251]
	global_store_dwordx4 v[154:155], v[80:83], off offset:192 nt
	s_nop 0
	v_add_co_u32_e32 v154, vcc, 0x10000, v154
	s_nop 1
	v_addc_co_u32_e32 v155, vcc, 0, v155, vcc
	global_load_dwordx4 v[250:253], v[150:151], off offset:64 nt
	s_waitcnt vmcnt(10)
	v_pk_fma_f32 v[78:79], v[78:79], v[140:141], v[166:167]
	v_pk_fma_f32 v[76:77], v[76:77], v[138:139], v[164:165]
	global_store_dwordx4 v[154:155], v[76:79], off nt
	global_load_dwordx4 v[164:167], v[150:151], off offset:128 nt
	s_waitcnt vmcnt(10)
	v_pk_fma_f32 v[74:75], v[74:75], v[144:145], v[170:171]
	v_pk_fma_f32 v[72:73], v[72:73], v[142:143], v[168:169]
	global_store_dwordx4 v[154:155], v[72:75], off offset:64 nt
	global_load_dwordx4 v[168:171], v[150:151], off offset:192 nt
	v_add_co_u32_e32 v150, vcc, 0x10000, v150
	s_nop 1
	v_addc_co_u32_e32 v151, vcc, 0, v151, vcc
	s_waitcnt vmcnt(10)
	v_pk_fma_f32 v[70:71], v[70:71], v[158:159], v[174:175]
	v_pk_fma_f32 v[68:69], v[68:69], v[156:157], v[172:173]
	global_store_dwordx4 v[154:155], v[68:71], off offset:128 nt
	global_load_dwordx4 v[172:175], v[150:151], off nt
	s_waitcnt vmcnt(10)
	v_pk_fma_f32 v[66:67], v[66:67], v[162:163], v[244:245]
	v_pk_fma_f32 v[64:65], v[64:65], v[160:161], v[242:243]
	global_store_dwordx4 v[154:155], v[64:67], off offset:192 nt
	s_nop 0
	v_add_co_u32_e32 v154, vcc, 0x10000, v154
	s_nop 1
	v_addc_co_u32_e32 v155, vcc, 0, v155, vcc
	global_load_dwordx4 v[242:245], v[150:151], off offset:64 nt
	s_waitcnt vmcnt(10)
	v_pk_fma_f32 v[62:63], v[62:63], v[140:141], v[248:249]
	v_pk_fma_f32 v[60:61], v[60:61], v[138:139], v[246:247]
	global_store_dwordx4 v[154:155], v[60:63], off nt
	global_load_dwordx4 v[246:249], v[150:151], off offset:128 nt
	s_waitcnt vmcnt(10)
	v_pk_fma_f32 v[58:59], v[58:59], v[144:145], v[252:253]
	v_pk_fma_f32 v[56:57], v[56:57], v[142:143], v[250:251]
	global_store_dwordx4 v[154:155], v[56:59], off offset:64 nt
	global_load_dwordx4 v[250:253], v[150:151], off offset:192 nt
	v_add_co_u32_e32 v150, vcc, 0x10000, v150
	s_nop 1
	v_addc_co_u32_e32 v151, vcc, 0, v151, vcc
	s_waitcnt vmcnt(10)
	v_pk_fma_f32 v[54:55], v[54:55], v[158:159], v[166:167]
	v_pk_fma_f32 v[52:53], v[52:53], v[156:157], v[164:165]
	global_store_dwordx4 v[154:155], v[52:55], off offset:128 nt
	global_load_dwordx4 v[164:167], v[150:151], off nt
	s_waitcnt vmcnt(10)
	v_pk_fma_f32 v[50:51], v[50:51], v[162:163], v[170:171]
	v_pk_fma_f32 v[48:49], v[48:49], v[160:161], v[168:169]
	global_store_dwordx4 v[154:155], v[48:51], off offset:192 nt
	s_nop 0
	v_add_co_u32_e32 v154, vcc, 0x10000, v154
	s_nop 1
	v_addc_co_u32_e32 v155, vcc, 0, v155, vcc
	global_load_dwordx4 v[168:171], v[150:151], off offset:64 nt
	s_waitcnt vmcnt(10)
	v_pk_fma_f32 v[46:47], v[46:47], v[140:141], v[174:175]
	v_pk_fma_f32 v[44:45], v[44:45], v[138:139], v[172:173]
	global_store_dwordx4 v[154:155], v[44:47], off nt
	global_load_dwordx4 v[172:175], v[150:151], off offset:128 nt
	s_waitcnt vmcnt(10)
	v_pk_fma_f32 v[42:43], v[42:43], v[144:145], v[244:245]
	v_pk_fma_f32 v[40:41], v[40:41], v[142:143], v[242:243]
	global_store_dwordx4 v[154:155], v[40:43], off offset:64 nt
	global_load_dwordx4 v[242:245], v[150:151], off offset:192 nt
	v_add_co_u32_e32 v150, vcc, 0x10000, v150
	s_nop 1
	v_addc_co_u32_e32 v151, vcc, 0, v151, vcc
	s_waitcnt vmcnt(10)
	v_pk_fma_f32 v[38:39], v[38:39], v[158:159], v[248:249]
	v_pk_fma_f32 v[36:37], v[36:37], v[156:157], v[246:247]
	global_store_dwordx4 v[154:155], v[36:39], off offset:128 nt
	global_load_dwordx4 v[246:249], v[150:151], off nt
	s_waitcnt vmcnt(10)
	v_pk_fma_f32 v[34:35], v[34:35], v[162:163], v[252:253]
	v_pk_fma_f32 v[32:33], v[32:33], v[160:161], v[250:251]
	global_store_dwordx4 v[154:155], v[32:35], off offset:192 nt
	s_nop 0
	v_add_co_u32_e32 v154, vcc, 0x10000, v154
	s_nop 1
	v_addc_co_u32_e32 v155, vcc, 0, v155, vcc
	global_load_dwordx4 v[250:253], v[150:151], off offset:64 nt
	s_waitcnt vmcnt(10)
	v_pk_fma_f32 v[30:31], v[30:31], v[140:141], v[166:167]
	v_pk_fma_f32 v[28:29], v[28:29], v[138:139], v[164:165]
	global_store_dwordx4 v[154:155], v[28:31], off nt
	global_load_dwordx4 v[164:167], v[150:151], off offset:128 nt
	s_waitcnt vmcnt(10)
	v_pk_fma_f32 v[22:23], v[22:23], v[144:145], v[170:171]
	v_pk_fma_f32 v[20:21], v[20:21], v[142:143], v[168:169]
	global_store_dwordx4 v[154:155], v[20:23], off offset:64 nt
	global_load_dwordx4 v[168:171], v[150:151], off offset:192 nt
	s_waitcnt vmcnt(10)
	v_pk_fma_f32 v[18:19], v[18:19], v[158:159], v[174:175]
	v_pk_fma_f32 v[16:17], v[16:17], v[156:157], v[172:173]
	global_store_dwordx4 v[154:155], v[16:19], off offset:128 nt
	s_waitcnt vmcnt(9)
	v_pk_fma_f32 v[14:15], v[14:15], v[162:163], v[244:245]
	v_pk_fma_f32 v[12:13], v[12:13], v[160:161], v[242:243]
	global_store_dwordx4 v[154:155], v[12:15], off offset:192 nt
	s_nop 0
	v_add_co_u32_e32 v154, vcc, 0x10000, v154
	s_nop 1
	v_addc_co_u32_e32 v155, vcc, 0, v155, vcc
	s_waitcnt vmcnt(8)
	v_pk_fma_f32 v[10:11], v[10:11], v[140:141], v[248:249]
	v_pk_fma_f32 v[8:9], v[8:9], v[138:139], v[246:247]
	global_store_dwordx4 v[154:155], v[8:11], off nt
	s_waitcnt vmcnt(7)
	v_pk_fma_f32 v[6:7], v[6:7], v[144:145], v[252:253]
	v_pk_fma_f32 v[4:5], v[4:5], v[142:143], v[250:251]
	global_store_dwordx4 v[154:155], v[4:7], off offset:64 nt
	s_waitcnt vmcnt(6)
	v_pk_fma_f32 v[2:3], v[2:3], v[158:159], v[166:167]
	v_pk_fma_f32 v[0:1], v[0:1], v[156:157], v[164:165]
	global_store_dwordx4 v[154:155], v[0:3], off offset:128 nt
	s_waitcnt vmcnt(5)
	v_pk_fma_f32 v[26:27], v[26:27], v[162:163], v[170:171]
	v_pk_fma_f32 v[24:25], v[24:25], v[160:161], v[168:169]
	global_store_dwordx4 v[154:155], v[24:27], off offset:192 nt
	s_branch .LBB0_763

.LBB0_1536:
	v_lshrrev_b32_e32 v131, 2, v198
	v_and_b32_e32 v130, 0xc0, v198
	v_and_b32_e32 v131, 12, v131
	v_or3_b32 v146, v130, v131, s8
	v_ashrrev_i32_e32 v130, 1, v198
	v_and_b32_e32 v130, 0xffffff80, v130
	v_lshl_add_u32 v134, s23, 8, v130
	v_and_or_b32 v132, v198, 15, v134
	v_ashrrev_i32_e32 v128, 13, v134
	v_mul_i32_i24_e32 v134, 0xc00, v128
	v_ashrrev_i32_e32 v133, 31, v132
	v_ashrrev_i32_e32 v135, 31, v134
	v_ashrrev_i32_e32 v147, 31, v146
	v_lshlrev_b64 v[130:131], 12, v[132:133]
	v_lshl_add_u64 v[134:135], v[134:135], 2, s[54:55]
	v_lshl_add_u64 v[134:135], v[134:135], 0, s[6:7]
	v_lshlrev_b64 v[136:137], 2, v[146:147]
	v_lshl_add_u64 v[148:149], v[134:135], 0, v[136:137]
	v_lshl_add_u64 v[150:151], s[52:53], 0, v[130:131]
	v_lshl_add_u64 v[150:151], v[150:151], 0, v[136:137]
	v_lshl_add_u64 v[154:155], s[52:53], 0, v[130:131]
	v_lshl_add_u64 v[154:155], v[154:155], 0, v[136:137]
	global_load_dwordx4 v[138:141], v[148:149], off
	global_load_dwordx4 v[142:145], v[148:149], off offset:64
	global_load_dwordx4 v[156:159], v[148:149], off offset:128
	global_load_dwordx4 v[160:163], v[148:149], off offset:192
	global_load_dwordx4 v[164:167], v[150:151], off nt
	global_load_dwordx4 v[168:171], v[150:151], off offset:64 nt
	global_load_dwordx4 v[172:175], v[150:151], off offset:128 nt
	global_load_dwordx4 v[242:245], v[150:151], off offset:192 nt
	v_add_co_u32_e32 v150, vcc, 0x10000, v150
	s_nop 1
	v_addc_co_u32_e32 v151, vcc, 0, v151, vcc
	global_load_dwordx4 v[246:249], v[150:151], off nt
	global_load_dwordx4 v[250:253], v[150:151], off offset:64 nt
	s_waitcnt vmcnt(5)
	v_pk_fma_f32 v[126:127], v[126:127], v[140:141], v[166:167]
	v_pk_fma_f32 v[124:125], v[124:125], v[138:139], v[164:165]
	global_store_dwordx4 v[154:155], v[124:127], off nt
	global_load_dwordx4 v[164:167], v[150:151], off offset:128 nt
	s_waitcnt vmcnt(6)
	v_pk_fma_f32 v[122:123], v[122:123], v[144:145], v[170:171]
	v_pk_fma_f32 v[120:121], v[120:121], v[142:143], v[168:169]
	global_store_dwordx4 v[154:155], v[120:123], off offset:64 nt
	global_load_dwordx4 v[168:171], v[150:151], off offset:192 nt
	v_add_co_u32_e32 v150, vcc, 0x10000, v150
	s_nop 1
	v_addc_co_u32_e32 v151, vcc, 0, v151, vcc
	s_waitcnt vmcnt(7)
	v_pk_fma_f32 v[118:119], v[118:119], v[158:159], v[174:175]
	v_pk_fma_f32 v[116:117], v[116:117], v[156:157], v[172:173]
	global_store_dwordx4 v[154:155], v[116:119], off offset:128 nt
	global_load_dwordx4 v[172:175], v[150:151], off nt
	s_waitcnt vmcnt(8)
	v_pk_fma_f32 v[114:115], v[114:115], v[162:163], v[244:245]
	v_pk_fma_f32 v[112:113], v[112:113], v[160:161], v[242:243]
	global_store_dwordx4 v[154:155], v[112:115], off offset:192 nt
	s_nop 0
	v_add_co_u32_e32 v154, vcc, 0x10000, v154
	s_nop 1
	v_addc_co_u32_e32 v155, vcc, 0, v155, vcc
	global_load_dwordx4 v[242:245], v[150:151], off offset:64 nt
	s_waitcnt vmcnt(9)
	v_pk_fma_f32 v[110:111], v[110:111], v[140:141], v[248:249]
	v_pk_fma_f32 v[108:109], v[108:109], v[138:139], v[246:247]
	global_store_dwordx4 v[154:155], v[108:111], off nt
	global_load_dwordx4 v[246:249], v[150:151], off offset:128 nt
	s_waitcnt vmcnt(10)
	v_pk_fma_f32 v[106:107], v[106:107], v[144:145], v[252:253]
	v_pk_fma_f32 v[104:105], v[104:105], v[142:143], v[250:251]
	global_store_dwordx4 v[154:155], v[104:107], off offset:64 nt
	global_load_dwordx4 v[250:253], v[150:151], off offset:192 nt
	v_add_co_u32_e32 v150, vcc, 0x10000, v150
	s_nop 1
	v_addc_co_u32_e32 v151, vcc, 0, v151, vcc
	s_waitcnt vmcnt(10)
	v_pk_fma_f32 v[102:103], v[102:103], v[158:159], v[166:167]
	v_pk_fma_f32 v[100:101], v[100:101], v[156:157], v[164:165]
	global_store_dwordx4 v[154:155], v[100:103], off offset:128 nt
	global_load_dwordx4 v[164:167], v[150:151], off nt
	s_waitcnt vmcnt(10)
	v_pk_fma_f32 v[98:99], v[98:99], v[162:163], v[170:171]
	v_pk_fma_f32 v[96:97], v[96:97], v[160:161], v[168:169]
	global_store_dwordx4 v[154:155], v[96:99], off offset:192 nt
	s_nop 0
	v_add_co_u32_e32 v154, vcc, 0x10000, v154
	s_nop 1
	v_addc_co_u32_e32 v155, vcc, 0, v155, vcc
	global_load_dwordx4 v[168:171], v[150:151], off offset:64 nt
	s_waitcnt vmcnt(10)
	v_pk_fma_f32 v[94:95], v[94:95], v[140:141], v[174:175]
	v_pk_fma_f32 v[92:93], v[92:93], v[138:139], v[172:173]
	global_store_dwordx4 v[154:155], v[92:95], off nt
	global_load_dwordx4 v[172:175], v[150:151], off offset:128 nt
	s_waitcnt vmcnt(10)
	v_pk_fma_f32 v[90:91], v[90:91], v[144:145], v[244:245]
	v_pk_fma_f32 v[88:89], v[88:89], v[142:143], v[242:243]
	global_store_dwordx4 v[154:155], v[88:91], off offset:64 nt
	global_load_dwordx4 v[242:245], v[150:151], off offset:192 nt
	v_add_co_u32_e32 v150, vcc, 0x10000, v150
	s_nop 1
	v_addc_co_u32_e32 v151, vcc, 0, v151, vcc
	s_waitcnt vmcnt(10)
	v_pk_fma_f32 v[86:87], v[86:87], v[158:159], v[248:249]
	v_pk_fma_f32 v[84:85], v[84:85], v[156:157], v[246:247]
	global_store_dwordx4 v[154:155], v[84:87], off offset:128 nt
	global_load_dwordx4 v[246:249], v[150:151], off nt
	s_waitcnt vmcnt(10)
	v_pk_fma_f32 v[82:83], v[82:83], v[162:163], v[252:253]
	v_pk_fma_f32 v[80:81], v[80:81], v[160:161], v[250:251]
	global_store_dwordx4 v[154:155], v[80:83], off offset:192 nt
	s_nop 0
	v_add_co_u32_e32 v154, vcc, 0x10000, v154
	s_nop 1
	v_addc_co_u32_e32 v155, vcc, 0, v155, vcc
	global_load_dwordx4 v[250:253], v[150:151], off offset:64 nt
	s_waitcnt vmcnt(10)
	v_pk_fma_f32 v[78:79], v[78:79], v[140:141], v[166:167]
	v_pk_fma_f32 v[76:77], v[76:77], v[138:139], v[164:165]
	global_store_dwordx4 v[154:155], v[76:79], off nt
	global_load_dwordx4 v[164:167], v[150:151], off offset:128 nt
	s_waitcnt vmcnt(10)
	v_pk_fma_f32 v[74:75], v[74:75], v[144:145], v[170:171]
	v_pk_fma_f32 v[72:73], v[72:73], v[142:143], v[168:169]
	global_store_dwordx4 v[154:155], v[72:75], off offset:64 nt
	global_load_dwordx4 v[168:171], v[150:151], off offset:192 nt
	v_add_co_u32_e32 v150, vcc, 0x10000, v150
	s_nop 1
	v_addc_co_u32_e32 v151, vcc, 0, v151, vcc
	s_waitcnt vmcnt(10)
	v_pk_fma_f32 v[70:71], v[70:71], v[158:159], v[174:175]
	v_pk_fma_f32 v[68:69], v[68:69], v[156:157], v[172:173]
	global_store_dwordx4 v[154:155], v[68:71], off offset:128 nt
	global_load_dwordx4 v[172:175], v[150:151], off nt
	s_waitcnt vmcnt(10)
	v_pk_fma_f32 v[66:67], v[66:67], v[162:163], v[244:245]
	v_pk_fma_f32 v[64:65], v[64:65], v[160:161], v[242:243]
	global_store_dwordx4 v[154:155], v[64:67], off offset:192 nt
	s_nop 0
	v_add_co_u32_e32 v154, vcc, 0x10000, v154
	s_nop 1
	v_addc_co_u32_e32 v155, vcc, 0, v155, vcc
	global_load_dwordx4 v[242:245], v[150:151], off offset:64 nt
	s_waitcnt vmcnt(10)
	v_pk_fma_f32 v[62:63], v[62:63], v[140:141], v[248:249]
	v_pk_fma_f32 v[60:61], v[60:61], v[138:139], v[246:247]
	global_store_dwordx4 v[154:155], v[60:63], off nt
	global_load_dwordx4 v[246:249], v[150:151], off offset:128 nt
	s_waitcnt vmcnt(10)
	v_pk_fma_f32 v[58:59], v[58:59], v[144:145], v[252:253]
	v_pk_fma_f32 v[56:57], v[56:57], v[142:143], v[250:251]
	global_store_dwordx4 v[154:155], v[56:59], off offset:64 nt
	global_load_dwordx4 v[250:253], v[150:151], off offset:192 nt
	v_add_co_u32_e32 v150, vcc, 0x10000, v150
	s_nop 1
	v_addc_co_u32_e32 v151, vcc, 0, v151, vcc
	s_waitcnt vmcnt(10)
	v_pk_fma_f32 v[54:55], v[54:55], v[158:159], v[166:167]
	v_pk_fma_f32 v[52:53], v[52:53], v[156:157], v[164:165]
	global_store_dwordx4 v[154:155], v[52:55], off offset:128 nt
	global_load_dwordx4 v[164:167], v[150:151], off nt
	s_waitcnt vmcnt(10)
	v_pk_fma_f32 v[50:51], v[50:51], v[162:163], v[170:171]
	v_pk_fma_f32 v[48:49], v[48:49], v[160:161], v[168:169]
	global_store_dwordx4 v[154:155], v[48:51], off offset:192 nt
	s_nop 0
	v_add_co_u32_e32 v154, vcc, 0x10000, v154
	s_nop 1
	v_addc_co_u32_e32 v155, vcc, 0, v155, vcc
	global_load_dwordx4 v[168:171], v[150:151], off offset:64 nt
	s_waitcnt vmcnt(10)
	v_pk_fma_f32 v[46:47], v[46:47], v[140:141], v[174:175]
	v_pk_fma_f32 v[44:45], v[44:45], v[138:139], v[172:173]
	global_store_dwordx4 v[154:155], v[44:47], off nt
	global_load_dwordx4 v[172:175], v[150:151], off offset:128 nt
	s_waitcnt vmcnt(10)
	v_pk_fma_f32 v[42:43], v[42:43], v[144:145], v[244:245]
	v_pk_fma_f32 v[40:41], v[40:41], v[142:143], v[242:243]
	global_store_dwordx4 v[154:155], v[40:43], off offset:64 nt
	global_load_dwordx4 v[242:245], v[150:151], off offset:192 nt
	v_add_co_u32_e32 v150, vcc, 0x10000, v150
	s_nop 1
	v_addc_co_u32_e32 v151, vcc, 0, v151, vcc
	s_waitcnt vmcnt(10)
	v_pk_fma_f32 v[38:39], v[38:39], v[158:159], v[248:249]
	v_pk_fma_f32 v[36:37], v[36:37], v[156:157], v[246:247]
	global_store_dwordx4 v[154:155], v[36:39], off offset:128 nt
	global_load_dwordx4 v[246:249], v[150:151], off nt
	s_waitcnt vmcnt(10)
	v_pk_fma_f32 v[34:35], v[34:35], v[162:163], v[252:253]
	v_pk_fma_f32 v[32:33], v[32:33], v[160:161], v[250:251]
	global_store_dwordx4 v[154:155], v[32:35], off offset:192 nt
	s_nop 0
	v_add_co_u32_e32 v154, vcc, 0x10000, v154
	s_nop 1
	v_addc_co_u32_e32 v155, vcc, 0, v155, vcc
	global_load_dwordx4 v[250:253], v[150:151], off offset:64 nt
	s_waitcnt vmcnt(10)
	v_pk_fma_f32 v[30:31], v[30:31], v[140:141], v[166:167]
	v_pk_fma_f32 v[28:29], v[28:29], v[138:139], v[164:165]
	global_store_dwordx4 v[154:155], v[28:31], off nt
	global_load_dwordx4 v[164:167], v[150:151], off offset:128 nt
	s_waitcnt vmcnt(10)
	v_pk_fma_f32 v[26:27], v[26:27], v[144:145], v[170:171]
	v_pk_fma_f32 v[24:25], v[24:25], v[142:143], v[168:169]
	global_store_dwordx4 v[154:155], v[24:27], off offset:64 nt
	global_load_dwordx4 v[168:171], v[150:151], off offset:192 nt
	s_waitcnt vmcnt(10)
	v_pk_fma_f32 v[18:19], v[18:19], v[158:159], v[174:175]
	v_pk_fma_f32 v[16:17], v[16:17], v[156:157], v[172:173]
	global_store_dwordx4 v[154:155], v[16:19], off offset:128 nt
	s_waitcnt vmcnt(9)
	v_pk_fma_f32 v[14:15], v[14:15], v[162:163], v[244:245]
	v_pk_fma_f32 v[12:13], v[12:13], v[160:161], v[242:243]
	global_store_dwordx4 v[154:155], v[12:15], off offset:192 nt
	s_nop 0
	v_add_co_u32_e32 v154, vcc, 0x10000, v154
	s_nop 1
	v_addc_co_u32_e32 v155, vcc, 0, v155, vcc
	s_waitcnt vmcnt(8)
	v_pk_fma_f32 v[10:11], v[10:11], v[140:141], v[248:249]
	v_pk_fma_f32 v[8:9], v[8:9], v[138:139], v[246:247]
	global_store_dwordx4 v[154:155], v[8:11], off nt
	s_waitcnt vmcnt(7)
	v_pk_fma_f32 v[6:7], v[6:7], v[144:145], v[252:253]
	v_pk_fma_f32 v[4:5], v[4:5], v[142:143], v[250:251]
	global_store_dwordx4 v[154:155], v[4:7], off offset:64 nt
	s_waitcnt vmcnt(6)
	v_pk_fma_f32 v[2:3], v[2:3], v[158:159], v[166:167]
	v_pk_fma_f32 v[0:1], v[0:1], v[156:157], v[164:165]
	global_store_dwordx4 v[154:155], v[0:3], off offset:128 nt
	s_waitcnt vmcnt(5)
	v_pk_fma_f32 v[22:23], v[22:23], v[162:163], v[170:171]
	v_pk_fma_f32 v[20:21], v[20:21], v[160:161], v[168:169]
	global_store_dwordx4 v[154:155], v[20:23], off offset:192 nt
	s_branch .LBB0_1529

.LBB0_1559:
	v_mov_b32_e32 v0, v198
	v_cmp_lt_i32_e32 vcc, v4, v3
	v_bfe_u32 v11, v0, 6, 2
	v_add_u32_e32 v12, s1, v11
	v_ashrrev_i32_e32 v13, 31, v12
	v_lshlrev_b32_e32 v0, 4, v0
	v_lshlrev_b64 v[12:13], 12, v[12:13]
	v_and_b32_e32 v0, 0x3f0, v0
	s_waitcnt lgkmcnt(0)
	v_lshl_add_u64 v[12:13], s[6:7], 0, v[12:13]
	v_lshl_add_u64 v[32:33], v[12:13], 0, v[0:1]
	global_load_dwordx4 v[12:15], v[32:33], off nt
	global_load_dwordx4 v[16:19], v[32:33], off offset:1024 nt
	global_load_dwordx4 v[20:23], v[32:33], off offset:2048 nt
	global_load_dwordx4 v[24:27], v[32:33], off offset:3072 nt
	v_cndmask_b32_e32 v11, v2, v4, vcc
	v_cmp_lt_i32_e32 vcc, v5, v3
	v_lshlrev_b32_e32 v11, 2, v11
	s_add_i32 s0, s0, s83
	v_cndmask_b32_e32 v28, v2, v5, vcc
	v_cmp_lt_i32_e32 vcc, v6, v3
	v_lshlrev_b32_e32 v50, 2, v28
	s_add_i32 s1, s1, s2
	v_cndmask_b32_e32 v29, v2, v6, vcc
	v_cmp_lt_i32_e32 vcc, v7, v3
	v_lshlrev_b32_e32 v51, 2, v29
	s_cmpk_lt_i32 s0, 0x1000
	v_cndmask_b32_e32 v30, v2, v7, vcc
	v_cmp_lt_i32_e32 vcc, v8, v3
	v_lshlrev_b32_e32 v52, 2, v30
	s_waitcnt vmcnt(3)
	v_mov_b32_e32 v36, v13
	v_cndmask_b32_e32 v31, v2, v8, vcc
	v_lshlrev_b32_e32 v53, 2, v31
	v_cmp_lt_i32_e32 vcc, v9, v3
	s_waitcnt vmcnt(2)
	v_mov_b32_e32 v37, v17
	v_mov_b32_e32 v35, v16
	v_cndmask_b32_e32 v34, v2, v9, vcc
	v_lshlrev_b32_e32 v54, 2, v34
	v_mov_b32_e32 v34, v12
	s_waitcnt vmcnt(1)
	v_mov_b32_e32 v44, v21
	s_waitcnt vmcnt(0)
	v_mov_b32_e32 v45, v25
	v_pk_mul_f32 v[36:37], v[36:37], v[36:37]
	v_mov_b32_e32 v38, v14
	v_mov_b32_e32 v39, v18
	v_mov_b32_e32 v42, v20
	v_mov_b32_e32 v43, v24
	v_pk_mul_f32 v[44:45], v[44:45], v[44:45]
	v_pk_fma_f32 v[34:35], v[34:35], v[34:35], v[36:37]
	v_mov_b32_e32 v40, v15
	v_mov_b32_e32 v41, v19
	v_mov_b32_e32 v46, v22
	v_mov_b32_e32 v47, v26
	v_pk_fma_f32 v[36:37], v[42:43], v[42:43], v[44:45]
	v_pk_fma_f32 v[34:35], v[38:39], v[38:39], v[34:35]
	v_mov_b32_e32 v48, v23
	v_mov_b32_e32 v49, v27
	v_pk_fma_f32 v[36:37], v[46:47], v[46:47], v[36:37]
	v_pk_fma_f32 v[34:35], v[40:41], v[40:41], v[34:35]
	v_pk_fma_f32 v[36:37], v[48:49], v[48:49], v[36:37]
	v_add_f32_e32 v34, v34, v35
	v_add_f32_e32 v34, v34, v36
	v_add_f32_e32 v34, v34, v37
	ds_bpermute_b32 v11, v11, v34
	s_waitcnt lgkmcnt(0)
	v_add_f32_e32 v11, v34, v11
	ds_bpermute_b32 v34, v50, v11
	s_waitcnt lgkmcnt(0)
	v_add_f32_e32 v11, v11, v34
	ds_bpermute_b32 v34, v51, v11
	s_waitcnt lgkmcnt(0)
	v_add_f32_e32 v11, v11, v34
	ds_bpermute_b32 v34, v52, v11
	s_waitcnt lgkmcnt(0)
	v_add_f32_e32 v11, v11, v34
	ds_bpermute_b32 v34, v53, v11
	s_waitcnt lgkmcnt(0)
	v_add_f32_e32 v11, v11, v34
	ds_bpermute_b32 v34, v54, v11
	s_waitcnt lgkmcnt(0)
	v_add_f32_e32 v11, v11, v34
	v_fmamk_f32 v11, v11, 0x3a800000, v10
	v_mul_f32_e32 v34, 0x4b800000, v11
	v_cmp_gt_f32_e32 vcc, s3, v11
	s_nop 1
	v_cndmask_b32_e32 v11, v11, v34, vcc
	v_rsq_f32_e32 v11, v11
	s_nop 0
	v_mul_f32_e32 v34, 0x45800000, v11
	v_cndmask_b32_e32 v34, v11, v34, vcc
	v_pk_mul_f32 v[12:13], v[12:13], v[34:35] op_sel_hi:[1,0]
	v_pk_mul_f32 v[14:15], v[14:15], v[34:35] op_sel_hi:[1,0]
	v_pk_mul_f32 v[12:13], v[68:69], v[12:13]
	v_pk_mul_f32 v[14:15], v[70:71], v[14:15]
	global_store_dwordx4 v[32:33], v[12:15], off nt
	v_pk_mul_f32 v[18:19], v[18:19], v[34:35] op_sel_hi:[1,0]
	v_pk_mul_f32 v[16:17], v[16:17], v[34:35] op_sel_hi:[1,0]
	v_pk_mul_f32 v[14:15], v[74:75], v[18:19]
	v_pk_mul_f32 v[12:13], v[72:73], v[16:17]
	global_store_dwordx4 v[32:33], v[12:15], off offset:1024 nt
	v_pk_mul_f32 v[16:17], v[22:23], v[34:35] op_sel_hi:[1,0]
	v_pk_mul_f32 v[18:19], v[20:21], v[34:35] op_sel_hi:[1,0]
	v_pk_mul_f32 v[14:15], v[78:79], v[16:17]
	v_pk_mul_f32 v[12:13], v[76:77], v[18:19]
	global_store_dwordx4 v[32:33], v[12:15], off offset:2048 nt
	v_pk_mul_f32 v[16:17], v[26:27], v[34:35] op_sel_hi:[1,0]
	v_pk_mul_f32 v[18:19], v[24:25], v[34:35] op_sel_hi:[1,0]
	v_pk_mul_f32 v[14:15], v[82:83], v[16:17]
	v_pk_mul_f32 v[12:13], v[80:81], v[18:19]
	global_store_dwordx4 v[32:33], v[12:15], off offset:3072 nt
	s_cbranch_scc1 .LBB0_1559
